# mixB sample item: LN gamma/beta and W/bias loads issued at the item top with the v/u and LN-partial loads
# baseline (speedup 1.0000x reference)
.LBB0_638:
	s_cmpk_gt_i32 s22, 0xff
	s_mov_b64 s[18:19], -1
	s_cbranch_scc0 .LBB0_640
	v_mov_b32_e32 v46, v195
	s_movk_i32 s18, 0x200
	v_ashrrev_i32_e32 v0, 6, v46
	v_add_u32_e32 v1, s3, v0
	v_ashrrev_i32_e32 v44, 1, v1
	v_lshlrev_b32_e32 v1, 3, v46
	v_lshlrev_b32_e32 v0, 9, v0
	v_and_b32_e32 v1, 0x1f8, v1
	v_and_or_b32 v45, v0, s18, v1
	v_lshlrev_b32_e32 v32, 3, v44
	v_lshlrev_b32_e32 v184, 1, v45
	v_add_u32_e32 v115, 0x2000, v32
	v_lshl_add_u64 v[0:1], s[12:13], 0, v[184:185]
	v_mad_i64_i32 v[2:3], s[18:19], v115, s68, v[0:1]
	v_add_co_u32_e32 v4, vcc, 0x1000, v2
	v_add_u32_e32 v114, 0x2001, v32
	s_nop 0
	v_addc_co_u32_e32 v5, vcc, 0, v3, vcc
	global_load_dwordx4 v[52:55], v[4:5], off
	global_load_dwordx4 v[28:31], v[2:3], off offset:2048
	v_mad_i64_i32 v[2:3], s[18:19], v114, s68, v[0:1]
	v_add_co_u32_e32 v4, vcc, 0x1000, v2
	v_add_u32_e32 v125, 0x2002, v32
	s_nop 0
	v_addc_co_u32_e32 v5, vcc, 0, v3, vcc
	global_load_dwordx4 v[60:63], v[4:5], off
	global_load_dwordx4 v[24:27], v[2:3], off offset:2048
	v_mad_i64_i32 v[2:3], s[18:19], v125, s68, v[0:1]
	v_add_co_u32_e32 v4, vcc, 0x1000, v2
	v_add_u32_e32 v124, 0x2003, v32
	s_nop 0
	v_addc_co_u32_e32 v5, vcc, 0, v3, vcc
	global_load_dwordx4 v[36:39], v[4:5], off
	global_load_dwordx4 v[20:23], v[2:3], off offset:2048
	v_mad_i64_i32 v[2:3], s[18:19], v124, s68, v[0:1]
	v_add_co_u32_e32 v4, vcc, 0x1000, v2
	v_add_u32_e32 v131, 0x2004, v32
	s_nop 0
	v_addc_co_u32_e32 v5, vcc, 0, v3, vcc
	global_load_dwordx4 v[64:67], v[4:5], off
	global_load_dwordx4 v[16:19], v[2:3], off offset:2048
	v_mad_i64_i32 v[2:3], s[18:19], v131, s68, v[0:1]
	v_add_co_u32_e32 v4, vcc, 0x1000, v2
	v_add_u32_e32 v130, 0x2005, v32
	s_nop 0
	v_addc_co_u32_e32 v5, vcc, 0, v3, vcc
	global_load_dwordx4 v[56:59], v[4:5], off
	global_load_dwordx4 v[12:15], v[2:3], off offset:2048
	v_mad_i64_i32 v[2:3], s[18:19], v130, s68, v[0:1]
	v_add_co_u32_e32 v4, vcc, 0x1000, v2
	v_add_u32_e32 v129, 0x2006, v32
	s_nop 0
	v_addc_co_u32_e32 v5, vcc, 0, v3, vcc
	global_load_dwordx4 v[48:51], v[4:5], off
	global_load_dwordx4 v[8:11], v[2:3], off offset:2048
	v_mad_i64_i32 v[2:3], s[18:19], v129, s68, v[0:1]
	v_add_co_u32_e32 v4, vcc, 0x1000, v2
	v_add_u32_e32 v128, 0x2007, v32
	v_and_or_b32 v46, v46, 7, v115
	v_addc_co_u32_e32 v5, vcc, 0, v3, vcc
	v_mad_i64_i32 v[0:1], s[18:19], v128, s68, v[0:1]
	v_ashrrev_i32_e32 v47, 31, v46
	global_load_dwordx4 v[40:43], v[4:5], off
	s_nop 0
	global_load_dwordx4 v[4:7], v[2:3], off offset:2048
	v_add_co_u32_e32 v2, vcc, 0x1000, v0
	v_lshlrev_b64 v[46:47], 7, v[46:47]
	s_nop 0
	v_addc_co_u32_e32 v3, vcc, 0, v1, vcc
	v_lshl_add_u64 v[46:47], s[14:15], 0, v[46:47]
	global_load_dwordx4 v[32:35], v[2:3], off
	s_nop 0
	global_load_dwordx4 v[0:3], v[0:1], off offset:2048
	s_nop 0
	global_load_dwordx4 v[68:71], v[46:47], off offset:48
	global_load_dwordx4 v[72:75], v[46:47], off offset:32
	global_load_dwordx4 v[76:79], v[46:47], off offset:16
	global_load_dwordx4 v[80:83], v[46:47], off
	global_load_dwordx4 v[84:87], v[46:47], off offset:112
	global_load_dwordx4 v[88:91], v[46:47], off offset:96
	global_load_dwordx4 v[92:95], v[46:47], off offset:80
	global_load_dwordx4 v[96:99], v[46:47], off offset:64
	s_load_dwordx8 s[72:79], s[80:81], 0xa0
	s_mov_b32 s18, 0x3a800000
	v_add_u32_e32 v44, s0, v44
	s_waitcnt lgkmcnt(0)
	s_lshl_b64 s[52:53], s[6:7], 2
	s_add_u32 s54, s74, s52
	s_addc_u32 s55, s75, s53
	s_add_u32 s52, s72, s52
	s_addc_u32 s53, s73, s53
	v_lshlrev_b32_e32 v230, 2, v45
	global_load_dwordx4 v[198:201], v230, s[52:53] offset:16
	global_load_dwordx4 v[202:205], v230, s[52:53]
	global_load_dwordx4 v[206:209], v230, s[54:55] offset:16
	global_load_dwordx4 v[210:213], v230, s[54:55]
	v_and_b32_e32 v226, 0x780, v184
	v_or_b32_e32 v228, s8, v226
	v_mov_b32_e32 v229, s9
	v_lshlrev_b64 v[226:227], 9, v[228:229]
	v_mov_b32_e32 v232, s78
	v_mov_b32_e32 v233, s79
	v_lshl_add_u64 v[228:229], v[228:229], 2, v[232:233]
	v_lshl_add_u64 v[226:227], s[76:77], 0, v[226:227]
	global_load_dword v224, v[228:229], off
	global_load_dword v225, v[226:227], off
	global_load_dword v146, v[228:229], off offset:4
	global_load_dwordx2 v[148:149], v[226:227], off offset:512
	global_load_dword v150, v[228:229], off offset:8
	global_load_dwordx3 v[152:154], v[226:227], off offset:1024
	global_load_dword v155, v[228:229], off offset:12
	global_load_dwordx4 v[156:159], v[226:227], off offset:1536
	global_load_dword v160, v[228:229], off offset:16
	global_load_dwordx4 v[162:165], v[226:227], off offset:2048
	global_load_dword v166, v[226:227], off offset:2064
	global_load_dword v167, v[228:229], off offset:20
	global_load_dwordx2 v[168:169], v[226:227], off offset:2576
	global_load_dwordx4 v[170:173], v[226:227], off offset:2560
	global_load_dword v174, v[228:229], off offset:24
	global_load_dwordx4 v[176:179], v[226:227], off offset:3072
	global_load_dwordx3 v[180:182], v[226:227], off offset:3088
	global_load_dword v183, v[228:229], off offset:28
	global_load_dwordx4 v[186:189], v[226:227], off offset:3600
	global_load_dwordx4 v[190:193], v[226:227], off offset:3584
	v_mov_b32_e32 v110, s78
	v_mov_b32_e32 v111, s79
	s_waitcnt vmcnt(44)
	v_lshlrev_b32_e32 v127, 16, v26
	v_and_b32_e32 v26, 0xffff0000, v26
	v_lshlrev_b32_e32 v132, 16, v27
	v_and_b32_e32 v27, 0xffff0000, v27
	s_waitcnt vmcnt(31)
	v_pk_add_f32 v[68:69], v[68:69], v[70:71]
	s_waitcnt vmcnt(30)
	v_pk_add_f32 v[72:73], v[72:73], v[74:75]
	s_waitcnt vmcnt(29)
	v_pk_add_f32 v[76:77], v[76:77], v[78:79]
	s_waitcnt vmcnt(28)
	v_pk_add_f32 v[46:47], v[80:81], v[82:83]
	v_lshlrev_b32_e32 v78, 16, v60
	v_pk_add_f32 v[46:47], v[46:47], 0 op_sel_hi:[1,0]
	v_and_b32_e32 v79, 0xffff0000, v60
	v_pk_add_f32 v[46:47], v[46:47], v[76:77]
	v_lshlrev_b32_e32 v60, 16, v61
	v_pk_add_f32 v[46:47], v[46:47], v[72:73]
	v_and_b32_e32 v61, 0xffff0000, v61
	v_pk_add_f32 v[46:47], v[46:47], v[68:69]
	s_waitcnt vmcnt(0)
	v_pk_add_f32 v[68:69], v[96:97], v[98:99]
	s_nop 0
	v_pk_add_f32 v[46:47], v[46:47], v[68:69]
	v_pk_add_f32 v[68:69], v[92:93], v[94:95]
	s_nop 0
	v_pk_add_f32 v[46:47], v[46:47], v[68:69]
	v_pk_add_f32 v[68:69], v[88:89], v[90:91]
	s_nop 0
	v_pk_add_f32 v[46:47], v[46:47], v[68:69]
	v_pk_add_f32 v[68:69], v[84:85], v[86:87]
	s_nop 0
	v_pk_add_f32 v[46:47], v[46:47], v[68:69]
	s_nop 0
	v_pk_mul_f32 v[108:109], v[46:47], s[18:19] op_sel_hi:[1,0]
	s_lshl_b64 s[18:19], s[6:7], 2
	v_fma_f32 v46, -v108, v108, v109
	s_add_u32 s20, s72, s18
	v_max_f32_e32 v46, 0, v46
	s_addc_u32 s21, s73, s19
	v_add_f32_e32 v72, 0x358637bd, v46
	v_lshlrev_b32_e32 v46, 2, v45
	s_add_u32 s18, s74, s18
	s_addc_u32 s19, s75, s19
	v_mov_b64_e32 v[84:85], v[198:199]
	v_mov_b64_e32 v[86:87], v[200:201]
	v_mov_b64_e32 v[68:69], v[202:203]
	v_mov_b64_e32 v[70:71], v[204:205]
	v_mov_b64_e32 v[88:89], v[206:207]
	v_mov_b64_e32 v[90:91], v[208:209]
	v_mov_b64_e32 v[92:93], v[210:211]
	v_mov_b64_e32 v[94:95], v[212:213]
	s_load_dwordx2 s[18:19], s[80:81], 0xf8
	v_ashrrev_i32_e32 v45, 31, v44
	v_lshlrev_b64 v[44:45], 15, v[44:45]
	v_mov_b32_e32 v47, v185
	v_rsq_f32_e32 v109, v72
	s_waitcnt lgkmcnt(0)
	v_lshl_add_u64 v[44:45], s[18:19], 0, v[44:45]
	v_lshl_add_u64 v[112:113], v[44:45], 0, v[46:47]
	v_lshlrev_b32_e32 v44, 2, v221
	v_and_b32_e32 v119, 0x100, v44
	ds_bpermute_b32 v74, v119, v108
	ds_bpermute_b32 v76, v119, v109
	s_mov_b64 s[18:19], 0x4a60000
	v_lshlrev_b32_e32 v44, 16, v52
	v_and_b32_e32 v45, 0xffff0000, v52
	v_lshlrev_b32_e32 v46, 16, v53
	v_and_b32_e32 v47, 0xffff0000, v53
	v_lshl_add_u64 v[72:73], v[112:113], 0, s[18:19]
	s_waitcnt lgkmcnt(1)
	v_pk_add_f32 v[44:45], v[44:45], v[74:75] op_sel_hi:[1,0] neg_lo:[0,1] neg_hi:[0,1]
	v_pk_add_f32 v[46:47], v[46:47], v[74:75] op_sel_hi:[1,0] neg_lo:[0,1] neg_hi:[0,1]
	v_lshlrev_b32_e32 v52, 16, v54
	v_and_b32_e32 v53, 0xffff0000, v54
	v_lshlrev_b32_e32 v54, 16, v55
	v_and_b32_e32 v55, 0xffff0000, v55
	s_mov_b32 s18, 0x4a61000
	s_waitcnt lgkmcnt(0)
	v_pk_mul_f32 v[44:45], v[44:45], v[76:77] op_sel_hi:[1,0]
	v_pk_mul_f32 v[46:47], v[46:47], v[76:77] op_sel_hi:[1,0]
	v_pk_add_f32 v[52:53], v[52:53], v[74:75] op_sel_hi:[1,0] neg_lo:[0,1] neg_hi:[0,1]
	v_pk_add_f32 v[54:55], v[54:55], v[74:75] op_sel_hi:[1,0] neg_lo:[0,1] neg_hi:[0,1]
	v_add_co_u32_e32 v74, vcc, s18, v112
	v_pk_mul_f32 v[52:53], v[52:53], v[76:77] op_sel_hi:[1,0]
	v_pk_mul_f32 v[54:55], v[54:55], v[76:77] op_sel_hi:[1,0]
	v_addc_co_u32_e32 v75, vcc, 0, v113, vcc
	ds_bpermute_b32 v76, v119, v109 offset:4
	s_mov_b32 s18, 0x4a62000
	ds_bpermute_b32 v118, v119, v109 offset:20
	s_waitcnt vmcnt(1)
	v_pk_fma_f32 v[52:53], v[84:85], v[52:53], v[88:89]
	s_waitcnt vmcnt(0)
	v_pk_fma_f32 v[44:45], v[68:69], v[44:45], v[92:93]
	v_pk_fma_f32 v[46:47], v[70:71], v[46:47], v[94:95]
	v_pk_fma_f32 v[54:55], v[86:87], v[54:55], v[90:91]
	global_store_dwordx4 v[74:75], v[44:47], off offset:-4096
	global_store_dwordx4 v[72:73], v[52:55], off offset:16
	ds_bpermute_b32 v72, v119, v108 offset:4
	s_waitcnt lgkmcnt(0)
	v_pk_add_f32 v[60:61], v[60:61], v[72:73] op_sel_hi:[1,0] neg_lo:[0,1] neg_hi:[0,1]
	s_nop 0
	v_pk_mul_f32 v[60:61], v[60:61], v[76:77] op_sel_hi:[1,0]
	v_pk_add_f32 v[78:79], v[78:79], v[72:73] op_sel_hi:[1,0] neg_lo:[0,1] neg_hi:[0,1]
	v_pk_fma_f32 v[106:107], v[70:71], v[60:61], v[94:95]
	v_lshlrev_b32_e32 v60, 16, v62
	v_and_b32_e32 v61, 0xffff0000, v62
	v_lshlrev_b32_e32 v62, 16, v63
	v_and_b32_e32 v63, 0xffff0000, v63
	v_pk_mul_f32 v[78:79], v[78:79], v[76:77] op_sel_hi:[1,0]
	v_pk_add_f32 v[60:61], v[60:61], v[72:73] op_sel_hi:[1,0] neg_lo:[0,1] neg_hi:[0,1]
	v_pk_add_f32 v[62:63], v[62:63], v[72:73] op_sel_hi:[1,0] neg_lo:[0,1] neg_hi:[0,1]
	v_pk_fma_f32 v[104:105], v[68:69], v[78:79], v[92:93]
	v_pk_mul_f32 v[60:61], v[60:61], v[76:77] op_sel_hi:[1,0]
	v_pk_mul_f32 v[62:63], v[62:63], v[76:77] op_sel_hi:[1,0]
	ds_bpermute_b32 v72, v119, v108 offset:8
	v_pk_fma_f32 v[60:61], v[84:85], v[60:61], v[88:89]
	v_pk_fma_f32 v[62:63], v[86:87], v[62:63], v[90:91]
	global_store_dwordx4 v[74:75], v[104:107], off
	global_store_dwordx4 v[74:75], v[60:63], off offset:16
	ds_bpermute_b32 v74, v119, v109 offset:8
	v_lshlrev_b32_e32 v76, 16, v36
	v_and_b32_e32 v77, 0xffff0000, v36
	v_lshlrev_b32_e32 v36, 16, v37
	v_and_b32_e32 v37, 0xffff0000, v37
	s_waitcnt lgkmcnt(1)
	v_pk_add_f32 v[36:37], v[36:37], v[72:73] op_sel_hi:[1,0] neg_lo:[0,1] neg_hi:[0,1]
	v_pk_add_f32 v[76:77], v[76:77], v[72:73] op_sel_hi:[1,0] neg_lo:[0,1] neg_hi:[0,1]
	s_waitcnt lgkmcnt(0)
	v_pk_mul_f32 v[36:37], v[36:37], v[74:75] op_sel_hi:[1,0]
	v_pk_mul_f32 v[76:77], v[76:77], v[74:75] op_sel_hi:[1,0]
	v_pk_fma_f32 v[102:103], v[70:71], v[36:37], v[94:95]
	v_lshlrev_b32_e32 v36, 16, v38
	v_and_b32_e32 v37, 0xffff0000, v38
	v_lshlrev_b32_e32 v38, 16, v39
	v_and_b32_e32 v39, 0xffff0000, v39
	v_pk_add_f32 v[36:37], v[36:37], v[72:73] op_sel_hi:[1,0] neg_lo:[0,1] neg_hi:[0,1]
	v_pk_add_f32 v[38:39], v[38:39], v[72:73] op_sel_hi:[1,0] neg_lo:[0,1] neg_hi:[0,1]
	v_add_co_u32_e32 v72, vcc, s18, v112
	s_mov_b32 s18, 0x4a63000
	s_nop 0
	v_addc_co_u32_e32 v73, vcc, 0, v113, vcc
	v_pk_mul_f32 v[36:37], v[36:37], v[74:75] op_sel_hi:[1,0]
	v_pk_mul_f32 v[38:39], v[38:39], v[74:75] op_sel_hi:[1,0]
	v_add_co_u32_e32 v74, vcc, s18, v112
	v_pk_fma_f32 v[100:101], v[68:69], v[76:77], v[92:93]
	s_nop 0
	v_addc_co_u32_e32 v75, vcc, 0, v113, vcc
	v_pk_fma_f32 v[36:37], v[84:85], v[36:37], v[88:89]
	v_pk_fma_f32 v[38:39], v[86:87], v[38:39], v[90:91]
	global_store_dwordx4 v[74:75], v[100:103], off offset:-4096
	global_store_dwordx4 v[72:73], v[36:39], off offset:16
	ds_bpermute_b32 v72, v119, v108 offset:12
	ds_bpermute_b32 v76, v119, v109 offset:12
	v_lshlrev_b32_e32 v78, 16, v64
	v_and_b32_e32 v79, 0xffff0000, v64
	v_lshlrev_b32_e32 v64, 16, v65
	v_and_b32_e32 v65, 0xffff0000, v65
	s_waitcnt lgkmcnt(1)
	v_pk_add_f32 v[64:65], v[64:65], v[72:73] op_sel_hi:[1,0] neg_lo:[0,1] neg_hi:[0,1]
	v_pk_add_f32 v[78:79], v[78:79], v[72:73] op_sel_hi:[1,0] neg_lo:[0,1] neg_hi:[0,1]
	s_waitcnt lgkmcnt(0)
	v_pk_mul_f32 v[64:65], v[64:65], v[76:77] op_sel_hi:[1,0]
	v_pk_mul_f32 v[78:79], v[78:79], v[76:77] op_sel_hi:[1,0]
	v_pk_fma_f32 v[98:99], v[70:71], v[64:65], v[94:95]
	v_lshlrev_b32_e32 v64, 16, v66
	v_and_b32_e32 v65, 0xffff0000, v66
	v_lshlrev_b32_e32 v66, 16, v67
	v_and_b32_e32 v67, 0xffff0000, v67
	v_pk_add_f32 v[64:65], v[64:65], v[72:73] op_sel_hi:[1,0] neg_lo:[0,1] neg_hi:[0,1]
	v_pk_add_f32 v[66:67], v[66:67], v[72:73] op_sel_hi:[1,0] neg_lo:[0,1] neg_hi:[0,1]
	v_pk_fma_f32 v[96:97], v[68:69], v[78:79], v[92:93]
	v_pk_mul_f32 v[64:65], v[64:65], v[76:77] op_sel_hi:[1,0]
	v_pk_mul_f32 v[66:67], v[66:67], v[76:77] op_sel_hi:[1,0]
	ds_bpermute_b32 v72, v119, v108 offset:16
	v_pk_fma_f32 v[64:65], v[84:85], v[64:65], v[88:89]
	v_pk_fma_f32 v[66:67], v[86:87], v[66:67], v[90:91]
	global_store_dwordx4 v[74:75], v[96:99], off
	global_store_dwordx4 v[74:75], v[64:67], off offset:16
	ds_bpermute_b32 v74, v119, v109 offset:16
	v_lshlrev_b32_e32 v76, 16, v56
	v_and_b32_e32 v77, 0xffff0000, v56
	v_lshlrev_b32_e32 v56, 16, v57
	v_and_b32_e32 v57, 0xffff0000, v57
	s_waitcnt lgkmcnt(1)
	v_pk_add_f32 v[56:57], v[56:57], v[72:73] op_sel_hi:[1,0] neg_lo:[0,1] neg_hi:[0,1]
	s_mov_b32 s18, 0x4a64000
	s_waitcnt lgkmcnt(0)
	v_pk_mul_f32 v[56:57], v[56:57], v[74:75] op_sel_hi:[1,0]
	v_pk_add_f32 v[76:77], v[76:77], v[72:73] op_sel_hi:[1,0] neg_lo:[0,1] neg_hi:[0,1]
	v_pk_fma_f32 v[82:83], v[70:71], v[56:57], v[94:95]
	v_lshlrev_b32_e32 v56, 16, v58
	v_and_b32_e32 v57, 0xffff0000, v58
	v_lshlrev_b32_e32 v58, 16, v59
	v_and_b32_e32 v59, 0xffff0000, v59
	v_pk_add_f32 v[56:57], v[56:57], v[72:73] op_sel_hi:[1,0] neg_lo:[0,1] neg_hi:[0,1]
	v_pk_add_f32 v[58:59], v[58:59], v[72:73] op_sel_hi:[1,0] neg_lo:[0,1] neg_hi:[0,1]
	v_add_co_u32_e32 v72, vcc, s18, v112
	ds_bpermute_b32 v78, v119, v108 offset:20
	s_nop 0
	v_addc_co_u32_e32 v73, vcc, 0, v113, vcc
	s_mov_b32 s18, 0x4a65000
	v_pk_mul_f32 v[76:77], v[76:77], v[74:75] op_sel_hi:[1,0]
	v_add_co_u32_e32 v116, vcc, s18, v112
	v_pk_fma_f32 v[80:81], v[68:69], v[76:77], v[92:93]
	v_pk_mul_f32 v[56:57], v[56:57], v[74:75] op_sel_hi:[1,0]
	v_pk_mul_f32 v[58:59], v[58:59], v[74:75] op_sel_hi:[1,0]
	v_addc_co_u32_e32 v117, vcc, 0, v113, vcc
	v_pk_fma_f32 v[56:57], v[84:85], v[56:57], v[88:89]
	v_pk_fma_f32 v[58:59], v[86:87], v[58:59], v[90:91]
	global_store_dwordx4 v[116:117], v[80:83], off offset:-4096
	global_store_dwordx4 v[72:73], v[56:59], off offset:16
	v_lshlrev_b32_e32 v72, 16, v48
	v_and_b32_e32 v73, 0xffff0000, v48
	v_lshlrev_b32_e32 v48, 16, v49
	v_and_b32_e32 v49, 0xffff0000, v49
	s_waitcnt lgkmcnt(0)
	v_pk_add_f32 v[48:49], v[48:49], v[78:79] op_sel_hi:[1,0] neg_lo:[0,1] neg_hi:[0,1]
	v_pk_add_f32 v[72:73], v[72:73], v[78:79] op_sel_hi:[1,0] neg_lo:[0,1] neg_hi:[0,1]
	v_pk_mul_f32 v[48:49], v[48:49], v[118:119] op_sel_hi:[1,0]
	v_pk_mul_f32 v[72:73], v[72:73], v[118:119] op_sel_hi:[1,0]
	v_pk_fma_f32 v[74:75], v[70:71], v[48:49], v[94:95]
	v_lshlrev_b32_e32 v48, 16, v50
	v_and_b32_e32 v49, 0xffff0000, v50
	v_pk_add_f32 v[48:49], v[48:49], v[78:79] op_sel_hi:[1,0] neg_lo:[0,1] neg_hi:[0,1]
	v_pk_fma_f32 v[72:73], v[68:69], v[72:73], v[92:93]
	v_pk_mul_f32 v[48:49], v[48:49], v[118:119] op_sel_hi:[1,0]
	s_mov_b32 s18, 0x4a66000
	v_pk_fma_f32 v[76:77], v[84:85], v[48:49], v[88:89]
	v_lshlrev_b32_e32 v48, 16, v51
	v_and_b32_e32 v49, 0xffff0000, v51
	v_pk_add_f32 v[48:49], v[48:49], v[78:79] op_sel_hi:[1,0] neg_lo:[0,1] neg_hi:[0,1]
	s_nop 0
	v_pk_mul_f32 v[48:49], v[48:49], v[118:119] op_sel_hi:[1,0]
	ds_bpermute_b32 v118, v119, v109 offset:24
	v_pk_fma_f32 v[78:79], v[86:87], v[48:49], v[90:91]
	global_store_dwordx4 v[116:117], v[72:75], off
	global_store_dwordx4 v[116:117], v[76:79], off offset:16
	ds_bpermute_b32 v116, v119, v108 offset:24
	v_lshlrev_b32_e32 v48, 16, v40
	v_and_b32_e32 v49, 0xffff0000, v40
	v_lshlrev_b32_e32 v40, 16, v41
	v_and_b32_e32 v41, 0xffff0000, v41
	s_waitcnt lgkmcnt(0)
	v_pk_add_f32 v[40:41], v[40:41], v[116:117] op_sel_hi:[1,0] neg_lo:[0,1] neg_hi:[0,1]
	v_pk_add_f32 v[48:49], v[48:49], v[116:117] op_sel_hi:[1,0] neg_lo:[0,1] neg_hi:[0,1]
	v_pk_mul_f32 v[40:41], v[40:41], v[118:119] op_sel_hi:[1,0]
	v_pk_mul_f32 v[48:49], v[48:49], v[118:119] op_sel_hi:[1,0]
	v_pk_fma_f32 v[50:51], v[70:71], v[40:41], v[94:95]
	v_lshlrev_b32_e32 v40, 16, v42
	v_and_b32_e32 v41, 0xffff0000, v42
	v_lshlrev_b32_e32 v42, 16, v43
	v_and_b32_e32 v43, 0xffff0000, v43
	v_pk_add_f32 v[40:41], v[40:41], v[116:117] op_sel_hi:[1,0] neg_lo:[0,1] neg_hi:[0,1]
	v_pk_add_f32 v[42:43], v[42:43], v[116:117] op_sel_hi:[1,0] neg_lo:[0,1] neg_hi:[0,1]
	v_add_co_u32_e32 v116, vcc, s18, v112
	s_mov_b32 s18, 0x4a67000
	s_nop 0
	v_addc_co_u32_e32 v117, vcc, 0, v113, vcc
	v_add_co_u32_e32 v112, vcc, s18, v112
	v_pk_fma_f32 v[48:49], v[68:69], v[48:49], v[92:93]
	v_pk_mul_f32 v[40:41], v[40:41], v[118:119] op_sel_hi:[1,0]
	v_pk_mul_f32 v[42:43], v[42:43], v[118:119] op_sel_hi:[1,0]
	v_addc_co_u32_e32 v113, vcc, 0, v113, vcc
	ds_bpermute_b32 v108, v119, v108 offset:28
	v_pk_fma_f32 v[40:41], v[84:85], v[40:41], v[88:89]
	v_pk_fma_f32 v[42:43], v[86:87], v[42:43], v[90:91]
	global_store_dwordx4 v[112:113], v[48:51], off offset:-4096
	global_store_dwordx4 v[116:117], v[40:43], off offset:16
	ds_bpermute_b32 v116, v119, v109 offset:28
	v_lshlrev_b32_e32 v118, 16, v32
	v_and_b32_e32 v119, 0xffff0000, v32
	v_lshlrev_b32_e32 v32, 16, v33
	v_and_b32_e32 v33, 0xffff0000, v33
	s_waitcnt lgkmcnt(1)
	v_pk_add_f32 v[32:33], v[32:33], v[108:109] op_sel_hi:[1,0] neg_lo:[0,1] neg_hi:[0,1]
	v_pk_add_f32 v[118:119], v[118:119], v[108:109] op_sel_hi:[1,0] neg_lo:[0,1] neg_hi:[0,1]
	s_waitcnt lgkmcnt(0)
	v_pk_mul_f32 v[32:33], v[32:33], v[116:117] op_sel_hi:[1,0]
	v_pk_mul_f32 v[118:119], v[118:119], v[116:117] op_sel_hi:[1,0]
	v_pk_fma_f32 v[70:71], v[70:71], v[32:33], v[94:95]
	v_lshlrev_b32_e32 v32, 16, v34
	v_and_b32_e32 v33, 0xffff0000, v34
	v_pk_add_f32 v[32:33], v[32:33], v[108:109] op_sel_hi:[1,0] neg_lo:[0,1] neg_hi:[0,1]
	v_lshlrev_b32_e32 v34, 16, v35
	v_and_b32_e32 v35, 0xffff0000, v35
	v_pk_mul_f32 v[32:33], v[32:33], v[116:117] op_sel_hi:[1,0]
	v_pk_add_f32 v[34:35], v[34:35], v[108:109] op_sel_hi:[1,0] neg_lo:[0,1] neg_hi:[0,1]
	v_pk_fma_f32 v[32:33], v[84:85], v[32:33], v[88:89]
	v_pk_mul_f32 v[34:35], v[34:35], v[116:117] op_sel_hi:[1,0]
	v_and_b32_e32 v84, 0x780, v184
	v_pk_fma_f32 v[68:69], v[68:69], v[118:119], v[92:93]
	v_pk_fma_f32 v[34:35], v[86:87], v[34:35], v[90:91]
	v_or_b32_e32 v86, s8, v84
	v_mov_b32_e32 v87, s9
	global_store_dwordx4 v[112:113], v[68:71], off
	global_store_dwordx4 v[112:113], v[32:35], off offset:16
	v_lshlrev_b64 v[84:85], 9, v[86:87]
	v_lshl_add_u64 v[86:87], v[86:87], 2, v[110:111]
	v_lshl_add_u64 v[84:85], s[76:77], 0, v[84:85]
	v_mov_b32_e32 v88, v224
	v_mov_b32_e32 v89, v225
	v_lshlrev_b32_e32 v109, 16, v29
	v_and_b32_e32 v29, 0xffff0000, v29
	v_lshlrev_b32_e32 v110, 16, v30
	v_and_b32_e32 v30, 0xffff0000, v30
	v_lshlrev_b32_e32 v111, 16, v31
	v_and_b32_e32 v31, 0xffff0000, v31
	s_waitcnt vmcnt(0)
	v_fma_f32 v90, v55, v89, v88
	v_fma_f32 v91, v44, v89, v88
	v_fma_f32 v92, v45, v89, v88
	v_fma_f32 v93, v46, v89, v88
	v_fma_f32 v94, v47, v89, v88
	v_fma_f32 v95, v52, v89, v88
	v_fma_f32 v108, v53, v89, v88
	v_fmac_f32_e32 v88, v54, v89
	v_lshlrev_b32_e32 v89, 16, v28
	v_and_b32_e32 v28, 0xffff0000, v28
	v_mul_f32_e32 v89, v91, v89
	v_mul_f32_e32 v28, v92, v28
	v_mul_f32_e32 v29, v94, v29
	v_mul_f32_e32 v91, v93, v109
	v_mul_f32_e32 v30, v108, v30
	v_mul_f32_e32 v93, v88, v111
	v_mul_f32_e32 v31, v90, v31
	v_cvt_pk_bf16_f32 v88, v89, v28
	v_cvt_pk_bf16_f32 v89, v91, v29
	v_mov_b64_e32 v[28:29], s[12:13]
	v_mul_f32_e32 v92, v95, v110
	v_cvt_pk_bf16_f32 v90, v92, v30
	v_cvt_pk_bf16_f32 v91, v93, v31
	v_mad_i64_i32 v[30:31], s[18:19], v115, s68, v[28:29]
	v_lshl_add_u64 v[30:31], v[30:31], 0, v[184:185]
	global_store_dwordx4 v[30:31], v[88:91], off offset:2048
	s_nop 1
	v_mov_b32_e32 v115, v146
	v_mov_b32_e32 v116, v148
	v_mov_b32_e32 v117, v149
	v_mov_b32_e32 v30, v55
	v_mov_b32_e32 v31, v63
	v_pk_mul_f32 v[88:89], v[30:31], v[116:117]
	s_nop 0
	v_add_f32_e32 v88, v115, v88
	v_add_f32_e32 v118, v88, v89
	v_mov_b32_e32 v88, v44
	v_mov_b32_e32 v89, v104
	v_pk_mul_f32 v[90:91], v[88:89], v[116:117]
	v_mul_f32_e32 v27, v118, v27
	v_add_f32_e32 v90, v115, v90
	v_add_f32_e32 v119, v90, v91
	v_mov_b32_e32 v90, v45
	v_mov_b32_e32 v91, v105
	v_pk_mul_f32 v[92:93], v[90:91], v[116:117]
	s_nop 0
	v_add_f32_e32 v92, v115, v92
	v_add_f32_e32 v120, v92, v93
	v_mov_b32_e32 v92, v46
	v_mov_b32_e32 v93, v106
	v_pk_mul_f32 v[94:95], v[92:93], v[116:117]
	s_nop 0
	v_add_f32_e32 v94, v115, v94
	v_add_f32_e32 v121, v94, v95
	v_mov_b32_e32 v94, v47
	v_mov_b32_e32 v95, v107
	v_pk_mul_f32 v[108:109], v[94:95], v[116:117]
	s_nop 0
	v_add_f32_e32 v108, v115, v108
	v_add_f32_e32 v122, v108, v109
	v_mov_b32_e32 v108, v52
	v_mov_b32_e32 v109, v60
	v_pk_mul_f32 v[110:111], v[108:109], v[116:117]
	s_nop 0
	v_add_f32_e32 v110, v115, v110
	v_add_f32_e32 v123, v110, v111
	v_mov_b32_e32 v110, v53
	v_mov_b32_e32 v111, v61
	v_pk_mul_f32 v[112:113], v[110:111], v[116:117]
	s_nop 0
	v_add_f32_e32 v112, v115, v112
	v_add_f32_e32 v126, v112, v113
	v_mov_b32_e32 v112, v54
	v_mov_b32_e32 v113, v62
	v_pk_mul_f32 v[116:117], v[112:113], v[116:117]
	v_mul_f32_e32 v26, v126, v26
	v_add_f32_e32 v115, v115, v116
	v_add_f32_e32 v115, v115, v117
	v_lshlrev_b32_e32 v116, 16, v24
	v_and_b32_e32 v24, 0xffff0000, v24
	v_lshlrev_b32_e32 v117, 16, v25
	v_and_b32_e32 v25, 0xffff0000, v25
	v_mul_f32_e32 v24, v120, v24
	v_mul_f32_e32 v25, v122, v25
	v_mul_f32_e32 v115, v115, v132
	v_mul_f32_e32 v116, v119, v116
	v_mul_f32_e32 v117, v121, v117
	v_mul_f32_e32 v119, v123, v127
	v_cvt_pk_bf16_f32 v24, v116, v24
	v_cvt_pk_bf16_f32 v25, v117, v25
	v_cvt_pk_bf16_f32 v26, v119, v26
	v_cvt_pk_bf16_f32 v27, v115, v27
	v_mad_i64_i32 v[114:115], s[18:19], v114, s68, v[28:29]
	v_lshl_add_u64 v[114:115], v[114:115], 0, v[184:185]
	global_store_dwordx4 v[114:115], v[24:27], off offset:2048
	s_nop 1
	v_mov_b32_e32 v27, v150
	s_nop 0
	s_nop 1
	v_mov_b32_e32 v24, v152
	v_mov_b32_e32 v25, v153
	v_mov_b32_e32 v26, v154
	v_mov_b32_e32 v114, v63
	v_mov_b32_e32 v115, v39
	v_mov_b32_e32 v116, v104
	v_mov_b32_e32 v117, v100
	v_mov_b32_e32 v104, v105
	v_mov_b32_e32 v105, v101
	v_mov_b32_e32 v123, v37
	v_mov_b32_e32 v63, v38
	v_mov_b32_e32 v126, v25
	v_mov_b32_e32 v127, v26
	v_fma_f32 v26, v55, v24, v27
	v_fma_f32 v118, v44, v24, v27
	v_fma_f32 v119, v45, v24, v27
	v_fma_f32 v120, v46, v24, v27
	v_fma_f32 v121, v47, v24, v27
	v_fma_f32 v122, v52, v24, v27
	v_fma_f32 v132, v53, v24, v27
	v_fmac_f32_e32 v27, v54, v24
	v_pk_mul_f32 v[24:25], v[114:115], v[126:127]
	s_nop 0
	v_add_f32_e32 v24, v26, v24
	v_add_f32_e32 v26, v24, v25
	v_pk_mul_f32 v[24:25], v[116:117], v[126:127]
	s_nop 0
	v_add_f32_e32 v24, v118, v24
	v_add_f32_e32 v133, v24, v25
	v_pk_mul_f32 v[24:25], v[104:105], v[126:127]
	v_mov_b32_e32 v118, v106
	v_add_f32_e32 v24, v119, v24
	v_mov_b32_e32 v119, v102
	v_add_f32_e32 v134, v24, v25
	v_pk_mul_f32 v[24:25], v[118:119], v[126:127]
	v_mov_b32_e32 v106, v107
	v_add_f32_e32 v24, v120, v24
	v_mov_b32_e32 v107, v103
	v_add_f32_e32 v135, v24, v25
	v_pk_mul_f32 v[24:25], v[106:107], v[126:127]
	v_mov_b32_e32 v120, v60
	v_add_f32_e32 v24, v121, v24
	v_mov_b32_e32 v121, v36
	v_add_f32_e32 v136, v24, v25
	v_pk_mul_f32 v[24:25], v[120:121], v[126:127]
	s_nop 0
	v_add_f32_e32 v24, v122, v24
	v_mov_b32_e32 v122, v61
	v_add_f32_e32 v60, v24, v25
	v_pk_mul_f32 v[24:25], v[122:123], v[126:127]
	s_nop 0
	v_add_f32_e32 v24, v132, v24
	v_add_f32_e32 v61, v24, v25
	v_pk_mul_f32 v[24:25], v[62:63], v[126:127]
	v_lshlrev_b32_e32 v126, 16, v22
	v_add_f32_e32 v24, v27, v24
	v_add_f32_e32 v24, v24, v25
	v_lshlrev_b32_e32 v25, 16, v20
	v_and_b32_e32 v20, 0xffff0000, v20
	v_lshlrev_b32_e32 v27, 16, v21
	v_and_b32_e32 v21, 0xffff0000, v21
	v_and_b32_e32 v22, 0xffff0000, v22
	v_lshlrev_b32_e32 v127, 16, v23
	v_and_b32_e32 v23, 0xffff0000, v23
	v_mul_f32_e32 v25, v133, v25
	v_mul_f32_e32 v20, v134, v20
	v_mul_f32_e32 v21, v136, v21
	v_mul_f32_e32 v22, v61, v22
	v_mul_f32_e32 v24, v24, v127
	v_mul_f32_e32 v23, v26, v23
	v_mul_f32_e32 v27, v135, v27
	v_mul_f32_e32 v60, v60, v126
	v_cvt_pk_bf16_f32 v20, v25, v20
	v_cvt_pk_bf16_f32 v21, v27, v21
	v_cvt_pk_bf16_f32 v22, v60, v22
	v_cvt_pk_bf16_f32 v23, v24, v23
	v_mad_i64_i32 v[24:25], s[18:19], v125, s68, v[28:29]
	v_lshl_add_u64 v[24:25], v[24:25], 0, v[184:185]
	global_store_dwordx4 v[24:25], v[20:23], off offset:2048
	s_nop 1
	v_mov_b32_e32 v22, v155
	s_nop 0
	s_nop 1
	v_mov_b32_e32 v132, v156
	v_mov_b32_e32 v133, v157
	v_mov_b32_e32 v134, v158
	v_mov_b32_e32 v135, v159
	v_pk_mul_f32 v[20:21], v[30:31], v[132:133]
	s_nop 0
	v_add_f32_e32 v20, v22, v20
	v_add_f32_e32 v24, v20, v21
	v_pk_mul_f32 v[20:21], v[88:89], v[132:133]
	s_nop 0
	v_add_f32_e32 v20, v22, v20
	v_add_f32_e32 v26, v20, v21
	v_pk_mul_f32 v[20:21], v[90:91], v[132:133]
	s_nop 0
	v_add_f32_e32 v20, v22, v20
	v_add_f32_e32 v60, v20, v21
	v_pk_mul_f32 v[20:21], v[92:93], v[132:133]
	s_nop 0
	v_add_f32_e32 v20, v22, v20
	v_add_f32_e32 v125, v20, v21
	v_pk_mul_f32 v[20:21], v[94:95], v[132:133]
	s_nop 0
	v_add_f32_e32 v20, v22, v20
	v_add_f32_e32 v126, v20, v21
	v_pk_mul_f32 v[20:21], v[108:109], v[132:133]
	s_nop 0
	v_add_f32_e32 v20, v22, v20
	v_add_f32_e32 v127, v20, v21
	v_pk_mul_f32 v[20:21], v[110:111], v[132:133]
	s_nop 0
	v_add_f32_e32 v20, v22, v20
	v_add_f32_e32 v136, v20, v21
	v_pk_mul_f32 v[20:21], v[112:113], v[132:133]
	s_nop 0
	v_add_f32_e32 v20, v22, v20
	v_add_f32_e32 v132, v20, v21
	v_mov_b32_e32 v20, v39
	v_mov_b32_e32 v21, v67
	v_pk_mul_f32 v[22:23], v[20:21], v[134:135]
	s_nop 0
	v_add_f32_e32 v22, v24, v22
	v_add_f32_e32 v133, v22, v23
	v_mov_b32_e32 v22, v100
	v_mov_b32_e32 v23, v96
	v_pk_mul_f32 v[24:25], v[22:23], v[134:135]
	s_nop 0
	v_add_f32_e32 v24, v26, v24
	v_add_f32_e32 v137, v24, v25
	v_mov_b32_e32 v24, v101
	v_mov_b32_e32 v25, v97
	v_pk_mul_f32 v[26:27], v[24:25], v[134:135]
	s_nop 0
	v_add_f32_e32 v26, v60, v26
	v_add_f32_e32 v138, v26, v27
	v_mov_b32_e32 v26, v102
	v_mov_b32_e32 v27, v98
	v_pk_mul_f32 v[60:61], v[26:27], v[134:135]
	s_nop 0
	v_add_f32_e32 v39, v125, v60
	v_add_f32_e32 v125, v39, v61
	v_mov_b32_e32 v60, v103
	v_mov_b32_e32 v61, v99
	v_pk_mul_f32 v[100:101], v[60:61], v[134:135]
	s_nop 0
	v_add_f32_e32 v39, v126, v100
	v_add_f32_e32 v126, v39, v101
	v_mov_b32_e32 v100, v36
	v_mov_b32_e32 v101, v64
	v_pk_mul_f32 v[102:103], v[100:101], v[134:135]
	s_nop 0
	v_add_f32_e32 v36, v127, v102
	v_add_f32_e32 v127, v36, v103
	v_mov_b32_e32 v36, v37
	v_mov_b32_e32 v37, v65
	v_pk_mul_f32 v[102:103], v[36:37], v[134:135]
	s_nop 0
	v_add_f32_e32 v39, v136, v102
	v_add_f32_e32 v136, v39, v103
	v_mov_b32_e32 v39, v66
	v_pk_mul_f32 v[102:103], v[38:39], v[134:135]
	v_lshlrev_b32_e32 v134, 16, v18
	v_add_f32_e32 v102, v132, v102
	v_add_f32_e32 v102, v102, v103
	v_lshlrev_b32_e32 v103, 16, v16
	v_and_b32_e32 v16, 0xffff0000, v16
	v_lshlrev_b32_e32 v132, 16, v17
	v_and_b32_e32 v17, 0xffff0000, v17
	v_and_b32_e32 v18, 0xffff0000, v18
	v_lshlrev_b32_e32 v135, 16, v19
	v_and_b32_e32 v19, 0xffff0000, v19
	v_mul_f32_e32 v103, v137, v103
	v_mul_f32_e32 v16, v138, v16
	v_mul_f32_e32 v17, v126, v17
	v_mul_f32_e32 v18, v136, v18
	v_mul_f32_e32 v102, v102, v135
	v_mul_f32_e32 v19, v133, v19
	v_mul_f32_e32 v125, v125, v132
	v_mul_f32_e32 v126, v127, v134
	v_cvt_pk_bf16_f32 v16, v103, v16
	v_cvt_pk_bf16_f32 v17, v125, v17
	v_cvt_pk_bf16_f32 v18, v126, v18
	v_cvt_pk_bf16_f32 v19, v102, v19
	v_mad_i64_i32 v[102:103], s[18:19], v124, s68, v[28:29]
	v_lshl_add_u64 v[102:103], v[102:103], 0, v[184:185]
	global_store_dwordx4 v[102:103], v[16:19], off offset:2048
	s_nop 1
	v_mov_b32_e32 v124, v160
	s_nop 0
	s_nop 1
	v_mov_b32_e32 v16, v162
	v_mov_b32_e32 v17, v163
	v_mov_b32_e32 v18, v164
	v_mov_b32_e32 v19, v165
	v_mov_b32_e32 v133, v166
	v_mov_b32_e32 v102, v17
	v_mov_b32_e32 v103, v18
	v_mov_b32_e32 v132, v19
	v_fma_f32 v18, v55, v16, v124
	v_fma_f32 v19, v44, v16, v124
	v_fma_f32 v125, v45, v16, v124
	v_fma_f32 v126, v46, v16, v124
	v_fma_f32 v127, v47, v16, v124
	v_fma_f32 v134, v52, v16, v124
	v_fma_f32 v135, v53, v16, v124
	v_fmac_f32_e32 v124, v54, v16
	v_pk_mul_f32 v[16:17], v[114:115], v[102:103]
	s_nop 0
	v_add_f32_e32 v16, v18, v16
	v_add_f32_e32 v18, v16, v17
	v_pk_mul_f32 v[16:17], v[116:117], v[102:103]
	s_nop 0
	v_add_f32_e32 v16, v19, v16
	v_add_f32_e32 v19, v16, v17
	v_pk_mul_f32 v[16:17], v[104:105], v[102:103]
	s_nop 0
	v_add_f32_e32 v16, v125, v16
	v_add_f32_e32 v136, v16, v17
	v_pk_mul_f32 v[16:17], v[118:119], v[102:103]
	v_mov_b32_e32 v125, v80
	v_add_f32_e32 v16, v126, v16
	v_add_f32_e32 v137, v16, v17
	v_pk_mul_f32 v[16:17], v[106:107], v[102:103]
	v_mov_b32_e32 v126, v98
	v_add_f32_e32 v16, v127, v16
	v_add_f32_e32 v138, v16, v17
	v_pk_mul_f32 v[16:17], v[120:121], v[102:103]
	v_mov_b32_e32 v127, v82
	v_add_f32_e32 v16, v134, v16
	v_add_f32_e32 v139, v16, v17
	v_pk_mul_f32 v[16:17], v[122:123], v[102:103]
	v_mov_b32_e32 v98, v99
	v_add_f32_e32 v16, v135, v16
	v_add_f32_e32 v140, v16, v17
	v_pk_mul_f32 v[16:17], v[62:63], v[102:103]
	v_mov_b32_e32 v102, v67
	v_add_f32_e32 v16, v124, v16
	v_mov_b32_e32 v103, v59
	v_add_f32_e32 v141, v16, v17
	v_pk_mul_f32 v[16:17], v[102:103], v[132:133]
	v_mov_b32_e32 v124, v96
	v_add_f32_e32 v16, v18, v16
	v_add_f32_e32 v18, v16, v17
	v_pk_mul_f32 v[16:17], v[124:125], v[132:133]
	v_mov_b32_e32 v96, v97
	v_add_f32_e32 v16, v19, v16
	v_mov_b32_e32 v97, v81
	v_add_f32_e32 v19, v16, v17
	v_pk_mul_f32 v[16:17], v[96:97], v[132:133]
	v_mov_b32_e32 v99, v83
	v_add_f32_e32 v16, v136, v16
	v_add_f32_e32 v142, v16, v17
	v_pk_mul_f32 v[16:17], v[126:127], v[132:133]
	v_mov_b32_e32 v134, v64
	v_add_f32_e32 v16, v137, v16
	v_add_f32_e32 v143, v16, v17
	v_pk_mul_f32 v[16:17], v[98:99], v[132:133]
	v_mov_b32_e32 v135, v56
	v_add_f32_e32 v16, v138, v16
	v_add_f32_e32 v138, v16, v17
	v_pk_mul_f32 v[16:17], v[134:135], v[132:133]
	v_mov_b32_e32 v136, v65
	v_add_f32_e32 v16, v139, v16
	v_mov_b32_e32 v137, v57
	v_add_f32_e32 v64, v16, v17
	v_pk_mul_f32 v[16:17], v[136:137], v[132:133]
	v_mov_b32_e32 v67, v58
	v_add_f32_e32 v16, v140, v16
	v_add_f32_e32 v65, v16, v17
	v_pk_mul_f32 v[16:17], v[66:67], v[132:133]
	v_lshlrev_b32_e32 v132, 16, v13
	v_add_f32_e32 v16, v141, v16
	v_add_f32_e32 v16, v16, v17
	v_lshlrev_b32_e32 v17, 16, v12
	v_and_b32_e32 v12, 0xffff0000, v12
	v_and_b32_e32 v13, 0xffff0000, v13
	v_lshlrev_b32_e32 v133, 16, v14
	v_and_b32_e32 v14, 0xffff0000, v14
	v_lshlrev_b32_e32 v139, 16, v15
	v_and_b32_e32 v15, 0xffff0000, v15
	v_mul_f32_e32 v17, v19, v17
	v_mul_f32_e32 v12, v142, v12
	v_mul_f32_e32 v13, v138, v13
	v_mul_f32_e32 v14, v65, v14
	v_mul_f32_e32 v16, v16, v139
	v_mul_f32_e32 v15, v18, v15
	v_mul_f32_e32 v19, v143, v132
	v_mul_f32_e32 v64, v64, v133
	v_cvt_pk_bf16_f32 v12, v17, v12
	v_cvt_pk_bf16_f32 v13, v19, v13
	v_cvt_pk_bf16_f32 v14, v64, v14
	v_cvt_pk_bf16_f32 v15, v16, v15
	v_mad_i64_i32 v[16:17], s[18:19], v131, s68, v[28:29]
	v_lshl_add_u64 v[16:17], v[16:17], 0, v[184:185]
	global_store_dwordx4 v[16:17], v[12:15], off offset:2048
	s_nop 1
	v_mov_b32_e32 v18, v167
	v_mov_b32_e32 v132, v168
	v_mov_b32_e32 v133, v169
	s_nop 0
	s_nop 1
	v_mov_b32_e32 v12, v170
	v_mov_b32_e32 v13, v171
	v_mov_b32_e32 v14, v172
	v_mov_b32_e32 v15, v173
	v_pk_mul_f32 v[16:17], v[30:31], v[12:13]
	s_nop 0
	v_add_f32_e32 v16, v18, v16
	v_add_f32_e32 v19, v16, v17
	v_pk_mul_f32 v[16:17], v[88:89], v[12:13]
	s_nop 0
	v_add_f32_e32 v16, v18, v16
	v_add_f32_e32 v64, v16, v17
	v_pk_mul_f32 v[16:17], v[90:91], v[12:13]
	s_nop 0
	v_add_f32_e32 v16, v18, v16
	v_add_f32_e32 v65, v16, v17
	v_pk_mul_f32 v[16:17], v[92:93], v[12:13]
	s_nop 0
	v_add_f32_e32 v16, v18, v16
	v_add_f32_e32 v131, v16, v17
	v_pk_mul_f32 v[16:17], v[94:95], v[12:13]
	s_nop 0
	v_add_f32_e32 v16, v18, v16
	v_add_f32_e32 v138, v16, v17
	v_pk_mul_f32 v[16:17], v[108:109], v[12:13]
	s_nop 0
	v_add_f32_e32 v16, v18, v16
	v_add_f32_e32 v139, v16, v17
	v_pk_mul_f32 v[16:17], v[110:111], v[12:13]
	v_pk_mul_f32 v[12:13], v[112:113], v[12:13]
	v_add_f32_e32 v16, v18, v16
	v_add_f32_e32 v12, v18, v12
	v_add_f32_e32 v16, v16, v17
	v_add_f32_e32 v17, v12, v13
	v_pk_mul_f32 v[12:13], v[20:21], v[14:15]
	s_nop 0
	v_add_f32_e32 v12, v19, v12
	v_add_f32_e32 v18, v12, v13
	v_pk_mul_f32 v[12:13], v[22:23], v[14:15]
	s_nop 0
	v_add_f32_e32 v12, v64, v12
	v_add_f32_e32 v19, v12, v13
	v_pk_mul_f32 v[12:13], v[24:25], v[14:15]
	s_nop 0
	v_add_f32_e32 v12, v65, v12
	v_add_f32_e32 v64, v12, v13
	v_pk_mul_f32 v[12:13], v[26:27], v[14:15]
	s_nop 0
	v_add_f32_e32 v12, v131, v12
	v_add_f32_e32 v131, v12, v13
	v_pk_mul_f32 v[12:13], v[60:61], v[14:15]
	s_nop 0
	v_add_f32_e32 v12, v138, v12
	v_add_f32_e32 v138, v12, v13
	v_pk_mul_f32 v[12:13], v[100:101], v[14:15]
	s_nop 0
	v_add_f32_e32 v12, v139, v12
	v_add_f32_e32 v139, v12, v13
	v_pk_mul_f32 v[12:13], v[36:37], v[14:15]
	s_nop 0
	v_add_f32_e32 v12, v16, v12
	v_add_f32_e32 v140, v12, v13
	v_pk_mul_f32 v[12:13], v[38:39], v[14:15]
	s_nop 0
	v_add_f32_e32 v12, v17, v12
	v_add_f32_e32 v141, v12, v13
	v_mov_b32_e32 v12, v59
	v_mov_b32_e32 v13, v79
	v_pk_mul_f32 v[14:15], v[12:13], v[132:133]
	s_nop 0
	v_add_f32_e32 v14, v18, v14
	v_add_f32_e32 v142, v14, v15
	v_mov_b32_e32 v14, v80
	v_mov_b32_e32 v15, v72
	v_pk_mul_f32 v[16:17], v[14:15], v[132:133]
	s_nop 0
	v_add_f32_e32 v16, v19, v16
	v_add_f32_e32 v143, v16, v17
	v_mov_b32_e32 v16, v81
	v_mov_b32_e32 v17, v73
	v_pk_mul_f32 v[18:19], v[16:17], v[132:133]
	s_nop 0
	v_add_f32_e32 v18, v64, v18
	v_add_f32_e32 v144, v18, v19
	v_mov_b32_e32 v18, v82
	v_mov_b32_e32 v19, v74
	v_pk_mul_f32 v[64:65], v[18:19], v[132:133]
	s_nop 0
	v_add_f32_e32 v59, v131, v64
	v_add_f32_e32 v131, v59, v65
	v_mov_b32_e32 v64, v83
	v_mov_b32_e32 v65, v75
	v_pk_mul_f32 v[80:81], v[64:65], v[132:133]
	s_nop 0
	v_add_f32_e32 v59, v138, v80
	v_add_f32_e32 v138, v59, v81
	v_mov_b32_e32 v80, v56
	v_mov_b32_e32 v81, v76
	v_pk_mul_f32 v[82:83], v[80:81], v[132:133]
	s_nop 0
	v_add_f32_e32 v56, v139, v82
	v_add_f32_e32 v139, v56, v83
	v_mov_b32_e32 v56, v57
	v_mov_b32_e32 v57, v77
	v_pk_mul_f32 v[82:83], v[56:57], v[132:133]
	s_nop 0
	v_add_f32_e32 v59, v140, v82
	v_add_f32_e32 v140, v59, v83
	v_mov_b32_e32 v59, v78
	v_pk_mul_f32 v[82:83], v[58:59], v[132:133]
	v_lshlrev_b32_e32 v132, 16, v9
	v_add_f32_e32 v82, v141, v82
	v_add_f32_e32 v82, v82, v83
	v_lshlrev_b32_e32 v83, 16, v8
	v_and_b32_e32 v8, 0xffff0000, v8
	v_and_b32_e32 v9, 0xffff0000, v9
	v_lshlrev_b32_e32 v133, 16, v10
	v_and_b32_e32 v10, 0xffff0000, v10
	v_lshlrev_b32_e32 v141, 16, v11
	v_and_b32_e32 v11, 0xffff0000, v11
	v_mul_f32_e32 v83, v143, v83
	v_mul_f32_e32 v8, v144, v8
	v_mul_f32_e32 v9, v138, v9
	v_mul_f32_e32 v10, v140, v10
	v_mul_f32_e32 v82, v82, v141
	v_mul_f32_e32 v11, v142, v11
	v_mul_f32_e32 v131, v131, v132
	v_mul_f32_e32 v132, v139, v133
	v_cvt_pk_bf16_f32 v8, v83, v8
	v_cvt_pk_bf16_f32 v9, v131, v9
	v_cvt_pk_bf16_f32 v10, v132, v10
	v_cvt_pk_bf16_f32 v11, v82, v11
	v_mad_i64_i32 v[82:83], s[18:19], v130, s68, v[28:29]
	v_lshl_add_u64 v[82:83], v[82:83], 0, v[184:185]
	global_store_dwordx4 v[82:83], v[8:11], off offset:2048
	s_nop 1
	v_mov_b32_e32 v133, v174
	s_nop 0
	s_nop 1
	v_mov_b32_e32 v8, v176
	v_mov_b32_e32 v9, v177
	v_mov_b32_e32 v10, v178
	v_mov_b32_e32 v11, v179
	v_mov_b32_e32 v130, v180
	v_mov_b32_e32 v131, v181
	v_mov_b32_e32 v132, v182
	v_mov_b32_e32 v82, v9
	v_mov_b32_e32 v83, v10
	v_fma_f32 v55, v55, v8, v133
	v_fma_f32 v44, v44, v8, v133
	v_fma_f32 v45, v45, v8, v133
	v_fma_f32 v46, v46, v8, v133
	v_fma_f32 v47, v47, v8, v133
	v_fma_f32 v52, v52, v8, v133
	v_fma_f32 v53, v53, v8, v133
	v_fmac_f32_e32 v133, v54, v8
	v_pk_mul_f32 v[8:9], v[114:115], v[82:83]
	v_mov_b32_e32 v10, v11
	v_add_f32_e32 v8, v55, v8
	v_add_f32_e32 v54, v8, v9
	v_pk_mul_f32 v[8:9], v[116:117], v[82:83]
	v_mov_b32_e32 v11, v130
	v_add_f32_e32 v8, v44, v8
	v_add_f32_e32 v44, v8, v9
	v_pk_mul_f32 v[8:9], v[104:105], v[82:83]
	v_mov_b32_e32 v130, v131
	v_add_f32_e32 v8, v45, v8
	v_add_f32_e32 v45, v8, v9
	v_pk_mul_f32 v[8:9], v[118:119], v[82:83]
	v_mov_b32_e32 v131, v132
	v_add_f32_e32 v8, v46, v8
	v_add_f32_e32 v46, v8, v9
	v_pk_mul_f32 v[8:9], v[106:107], v[82:83]
	s_nop 0
	v_add_f32_e32 v8, v47, v8
	v_add_f32_e32 v47, v8, v9
	v_pk_mul_f32 v[8:9], v[120:121], v[82:83]
	s_nop 0
	v_add_f32_e32 v8, v52, v8
	v_add_f32_e32 v52, v8, v9
	v_pk_mul_f32 v[8:9], v[122:123], v[82:83]
	s_nop 0
	v_add_f32_e32 v8, v53, v8
	v_add_f32_e32 v53, v8, v9
	v_pk_mul_f32 v[8:9], v[62:63], v[82:83]
	s_nop 0
	v_add_f32_e32 v8, v133, v8
	v_add_f32_e32 v55, v8, v9
	v_pk_mul_f32 v[8:9], v[102:103], v[10:11]
	s_nop 0
	v_add_f32_e32 v8, v54, v8
	v_add_f32_e32 v54, v8, v9
	v_pk_mul_f32 v[8:9], v[124:125], v[10:11]
	s_nop 0
	v_add_f32_e32 v8, v44, v8
	v_add_f32_e32 v44, v8, v9
	v_pk_mul_f32 v[8:9], v[96:97], v[10:11]
	s_nop 0
	v_add_f32_e32 v8, v45, v8
	v_add_f32_e32 v45, v8, v9
	v_pk_mul_f32 v[8:9], v[126:127], v[10:11]
	s_nop 0
	v_add_f32_e32 v8, v46, v8
	v_add_f32_e32 v46, v8, v9
	v_pk_mul_f32 v[8:9], v[98:99], v[10:11]
	s_nop 0
	v_add_f32_e32 v8, v47, v8
	v_add_f32_e32 v47, v8, v9
	v_pk_mul_f32 v[8:9], v[134:135], v[10:11]
	s_nop 0
	v_add_f32_e32 v8, v52, v8
	v_add_f32_e32 v52, v8, v9
	v_pk_mul_f32 v[8:9], v[136:137], v[10:11]
	s_nop 0
	v_add_f32_e32 v8, v53, v8
	v_add_f32_e32 v53, v8, v9
	v_pk_mul_f32 v[8:9], v[66:67], v[10:11]
	s_nop 0
	v_add_f32_e32 v8, v55, v8
	v_add_f32_e32 v10, v8, v9
	v_mov_b32_e32 v8, v79
	v_mov_b32_e32 v9, v43
	v_pk_mul_f32 v[8:9], v[8:9], v[130:131]
	v_mov_b32_e32 v79, v42
	v_add_f32_e32 v8, v54, v8
	v_add_f32_e32 v11, v8, v9
	v_mov_b32_e32 v8, v72
	v_mov_b32_e32 v9, v48
	v_pk_mul_f32 v[8:9], v[8:9], v[130:131]
	v_lshlrev_b32_e32 v54, 16, v6
	v_add_f32_e32 v8, v44, v8
	v_add_f32_e32 v44, v8, v9
	v_mov_b32_e32 v8, v73
	v_mov_b32_e32 v9, v49
	v_pk_mul_f32 v[8:9], v[8:9], v[130:131]
	v_and_b32_e32 v6, 0xffff0000, v6
	v_add_f32_e32 v8, v45, v8
	v_add_f32_e32 v45, v8, v9
	v_mov_b32_e32 v8, v74
	v_mov_b32_e32 v9, v50
	v_pk_mul_f32 v[8:9], v[8:9], v[130:131]
	v_lshlrev_b32_e32 v55, 16, v7
	v_add_f32_e32 v8, v46, v8
	v_add_f32_e32 v46, v8, v9
	v_mov_b32_e32 v8, v75
	v_mov_b32_e32 v9, v51
	v_pk_mul_f32 v[8:9], v[8:9], v[130:131]
	v_and_b32_e32 v7, 0xffff0000, v7
	v_add_f32_e32 v8, v47, v8
	v_add_f32_e32 v47, v8, v9
	v_mov_b32_e32 v8, v76
	v_mov_b32_e32 v9, v40
	v_pk_mul_f32 v[8:9], v[8:9], v[130:131]
	v_mul_f32_e32 v7, v11, v7
	v_add_f32_e32 v8, v52, v8
	v_add_f32_e32 v52, v8, v9
	v_mov_b32_e32 v8, v77
	v_mov_b32_e32 v9, v41
	v_pk_mul_f32 v[8:9], v[8:9], v[130:131]
	s_nop 0
	v_add_f32_e32 v8, v53, v8
	v_add_f32_e32 v53, v8, v9
	v_pk_mul_f32 v[8:9], v[78:79], v[130:131]
	v_mul_f32_e32 v6, v53, v6
	v_add_f32_e32 v8, v10, v8
	v_add_f32_e32 v8, v8, v9
	v_lshlrev_b32_e32 v9, 16, v4
	v_and_b32_e32 v4, 0xffff0000, v4
	v_lshlrev_b32_e32 v10, 16, v5
	v_and_b32_e32 v5, 0xffff0000, v5
	v_mul_f32_e32 v9, v44, v9
	v_mul_f32_e32 v4, v45, v4
	v_mul_f32_e32 v5, v47, v5
	v_mul_f32_e32 v8, v8, v55
	v_mul_f32_e32 v10, v46, v10
	v_mul_f32_e32 v44, v52, v54
	v_cvt_pk_bf16_f32 v4, v9, v4
	v_cvt_pk_bf16_f32 v5, v10, v5
	v_cvt_pk_bf16_f32 v6, v44, v6
	v_cvt_pk_bf16_f32 v7, v8, v7
	v_mad_i64_i32 v[8:9], s[18:19], v129, s68, v[28:29]
	v_lshl_add_u64 v[8:9], v[8:9], 0, v[184:185]
	global_store_dwordx4 v[8:9], v[4:7], off offset:2048
	s_nop 1
	v_mov_b32_e32 v44, v183
	s_nop 0
	s_nop 1
	v_mov_b32_e32 v4, v186
	v_mov_b32_e32 v5, v187
	v_mov_b32_e32 v6, v188
	v_mov_b32_e32 v7, v189
	v_mov_b32_e32 v8, v190
	v_mov_b32_e32 v9, v191
	v_mov_b32_e32 v10, v192
	v_mov_b32_e32 v11, v193
	v_pk_mul_f32 v[30:31], v[30:31], v[8:9]
	s_nop 0
	v_add_f32_e32 v30, v44, v30
	v_add_f32_e32 v45, v30, v31
	v_pk_mul_f32 v[30:31], v[88:89], v[8:9]
	s_nop 0
	v_add_f32_e32 v30, v44, v30
	v_add_f32_e32 v46, v30, v31
	v_pk_mul_f32 v[30:31], v[90:91], v[8:9]
	s_nop 0
	v_add_f32_e32 v30, v44, v30
	v_add_f32_e32 v47, v30, v31
	v_pk_mul_f32 v[30:31], v[92:93], v[8:9]
	s_nop 0
	v_add_f32_e32 v30, v44, v30
	v_add_f32_e32 v52, v30, v31
	v_pk_mul_f32 v[30:31], v[94:95], v[8:9]
	s_nop 0
	v_add_f32_e32 v30, v44, v30
	v_add_f32_e32 v53, v30, v31
	v_pk_mul_f32 v[30:31], v[108:109], v[8:9]
	s_nop 0
	v_add_f32_e32 v30, v44, v30
	v_add_f32_e32 v54, v30, v31
	v_pk_mul_f32 v[30:31], v[110:111], v[8:9]
	v_pk_mul_f32 v[8:9], v[112:113], v[8:9]
	v_add_f32_e32 v30, v44, v30
	v_add_f32_e32 v8, v44, v8
	v_add_f32_e32 v30, v30, v31
	v_add_f32_e32 v31, v8, v9
	v_pk_mul_f32 v[8:9], v[20:21], v[10:11]
	s_nop 0
	v_add_f32_e32 v8, v45, v8
	v_add_f32_e32 v20, v8, v9
	v_pk_mul_f32 v[8:9], v[22:23], v[10:11]
	s_nop 0
	v_add_f32_e32 v8, v46, v8
	v_add_f32_e32 v21, v8, v9
	v_pk_mul_f32 v[8:9], v[24:25], v[10:11]
	s_nop 0
	v_add_f32_e32 v8, v47, v8
	v_add_f32_e32 v22, v8, v9
	v_pk_mul_f32 v[8:9], v[26:27], v[10:11]
	s_nop 0
	v_add_f32_e32 v8, v52, v8
	v_add_f32_e32 v23, v8, v9
	v_pk_mul_f32 v[8:9], v[60:61], v[10:11]
	s_nop 0
	v_add_f32_e32 v8, v53, v8
	v_add_f32_e32 v24, v8, v9
	v_pk_mul_f32 v[8:9], v[100:101], v[10:11]
	s_nop 0
	v_add_f32_e32 v8, v54, v8
	v_add_f32_e32 v25, v8, v9
	v_pk_mul_f32 v[8:9], v[36:37], v[10:11]
	s_nop 0
	v_add_f32_e32 v8, v30, v8
	v_add_f32_e32 v26, v8, v9
	v_pk_mul_f32 v[8:9], v[38:39], v[10:11]
	s_nop 0
	v_add_f32_e32 v8, v31, v8
	v_add_f32_e32 v10, v8, v9
	v_pk_mul_f32 v[8:9], v[12:13], v[4:5]
	s_nop 0
	v_add_f32_e32 v8, v20, v8
	v_add_f32_e32 v11, v8, v9
	v_pk_mul_f32 v[8:9], v[14:15], v[4:5]
	s_nop 0
	v_add_f32_e32 v8, v21, v8
	v_add_f32_e32 v12, v8, v9
	v_pk_mul_f32 v[8:9], v[16:17], v[4:5]
	s_nop 0
	v_add_f32_e32 v8, v22, v8
	v_add_f32_e32 v13, v8, v9
	v_pk_mul_f32 v[8:9], v[18:19], v[4:5]
	s_nop 0
	v_add_f32_e32 v8, v23, v8
	v_add_f32_e32 v14, v8, v9
	v_pk_mul_f32 v[8:9], v[64:65], v[4:5]
	s_nop 0
	v_add_f32_e32 v8, v24, v8
	v_add_f32_e32 v15, v8, v9
	v_pk_mul_f32 v[8:9], v[80:81], v[4:5]
	s_nop 0
	v_add_f32_e32 v8, v25, v8
	v_add_f32_e32 v16, v8, v9
	v_pk_mul_f32 v[8:9], v[56:57], v[4:5]
	v_pk_mul_f32 v[4:5], v[58:59], v[4:5]
	v_add_f32_e32 v8, v26, v8
	v_add_f32_e32 v4, v10, v4
	v_add_f32_e32 v8, v8, v9
	v_add_f32_e32 v9, v4, v5
	v_mov_b32_e32 v4, v43
	v_mov_b32_e32 v5, v35
	v_pk_mul_f32 v[4:5], v[4:5], v[6:7]
	v_mov_b32_e32 v43, v34
	v_add_f32_e32 v4, v11, v4
	v_add_f32_e32 v10, v4, v5
	v_mov_b32_e32 v4, v48
	v_mov_b32_e32 v5, v68
	v_pk_mul_f32 v[4:5], v[4:5], v[6:7]
	v_mov_b32_e32 v68, v49
	v_add_f32_e32 v4, v12, v4
	v_add_f32_e32 v11, v4, v5
	v_pk_mul_f32 v[4:5], v[68:69], v[6:7]
	s_nop 0
	v_add_f32_e32 v4, v13, v4
	v_add_f32_e32 v12, v4, v5
	v_mov_b32_e32 v4, v50
	v_mov_b32_e32 v5, v70
	v_pk_mul_f32 v[4:5], v[4:5], v[6:7]
	v_mov_b32_e32 v70, v51
	v_add_f32_e32 v4, v14, v4
	v_add_f32_e32 v13, v4, v5
	v_pk_mul_f32 v[4:5], v[70:71], v[6:7]
	s_nop 0
	v_add_f32_e32 v4, v15, v4
	v_add_f32_e32 v14, v4, v5
	v_mov_b32_e32 v4, v40
	v_mov_b32_e32 v5, v32
	v_pk_mul_f32 v[4:5], v[4:5], v[6:7]
	v_mov_b32_e32 v32, v41
	v_add_f32_e32 v4, v16, v4
	v_add_f32_e32 v15, v4, v5
	v_pk_mul_f32 v[4:5], v[32:33], v[6:7]
	s_nop 0
	v_add_f32_e32 v4, v8, v4
	v_add_f32_e32 v8, v4, v5
	v_pk_mul_f32 v[4:5], v[42:43], v[6:7]
	v_lshlrev_b32_e32 v6, 16, v1
	v_add_f32_e32 v4, v9, v4
	v_add_f32_e32 v4, v4, v5
	v_lshlrev_b32_e32 v5, 16, v0
	v_and_b32_e32 v0, 0xffff0000, v0
	v_and_b32_e32 v1, 0xffff0000, v1
	v_lshlrev_b32_e32 v7, 16, v2
	v_and_b32_e32 v2, 0xffff0000, v2
	v_lshlrev_b32_e32 v9, 16, v3
	v_and_b32_e32 v3, 0xffff0000, v3
	v_mul_f32_e32 v5, v11, v5
	v_mul_f32_e32 v0, v12, v0
	v_mul_f32_e32 v1, v14, v1
	v_mul_f32_e32 v2, v8, v2
	v_mul_f32_e32 v4, v4, v9
	v_mul_f32_e32 v3, v10, v3
	v_mul_f32_e32 v6, v13, v6
	v_mul_f32_e32 v7, v15, v7
	v_cvt_pk_bf16_f32 v0, v5, v0
	v_cvt_pk_bf16_f32 v1, v6, v1
	v_cvt_pk_bf16_f32 v2, v7, v2
	v_cvt_pk_bf16_f32 v3, v4, v3
	v_mad_i64_i32 v[4:5], s[18:19], v128, s68, v[28:29]
	v_lshl_add_u64 v[4:5], v[4:5], 0, v[184:185]
	global_store_dwordx4 v[4:5], v[0:3], off offset:2048
	s_mov_b64 s[18:19], 0
